# v40 + GEMM phase prologue: K-tile-1 DMAs issued together with K-tile-0 (both cold round trips overlap)
# baseline (speedup 1.0000x reference)
.LBB0_203:
	s_add_u32 s52, s4, s6
	s_addc_u32 s4, s5, s7
	s_and_b32 s53, s4, 0xffff
	s_mul_hi_i32 s4, s14, s46
	s_mul_i32 s14, s14, s46
	s_add_u32 s56, s2, s14
	s_addc_u32 s2, s3, s4
	s_and_b32 s57, s2, 0xffff
	s_lshr_b32 s2, s0, 1
	s_lshr_b32 s47, s1, 6
	s_lshl_b32 s3, s1, 1
	s_and_b32 s2, s2, 0x1ffff80
	s_and_b32 s0, s0, 0xc0
	v_bfe_u32 v3, v0, 4, 2
	v_bfe_u32 v4, v0, 3, 3
	s_add_u32 s24, s26, 0x11884000
	v_mul_u32_u24_e32 v4, s3, v4
	v_bitop3_b32 v6, v3, v0, 7 bitop3:0x78
	s_addc_u32 s25, s27, 0
	s_lshl_b32 s76, s12, 12
	s_mov_b32 s58, s54
	s_mov_b32 s59, s55
	v_and_b32_e32 v5, 7, v0
	v_lshl_or_b32 v227, v6, 4, v4
	s_mul_i32 s96, s13, s3
	s_mov_b32 m0, s76
	s_add_i32 s97, s76, 0x8000
	v_bitop3_b32 v5, v3, v5, 4 bitop3:0x36
	s_barrier
	s_mul_i32 s5, s8, s3
	buffer_load_dwordx4 v227, s[56:59], s96 offen lds
	s_mov_b32 m0, s97
	s_lshl_b32 s16, s1, 4
	s_or_b32 s94, s76, 0x400
	v_and_b32_e32 v2, 15, v0
	v_lshl_or_b32 v229, v5, 4, v4
	buffer_load_dwordx4 v227, s[52:55], s5 offen lds
	s_add_i32 s12, s96, s16
	s_mov_b32 m0, s94
	s_add_i32 s95, s76, 0x8400
	v_or_b32_e32 v5, s2, v2
	s_add_i32 s2, s5, s16
	buffer_load_dwordx4 v229, s[56:59], s12 offen lds
	s_mov_b32 m0, s95
	s_or_b32 s87, s76, 0x800
	buffer_load_dwordx4 v229, s[52:55], s2 offen lds
	s_add_i32 s86, s12, s16
	s_mov_b32 m0, s87
	s_add_i32 s20, s76, 0x8800
	s_add_i32 s2, s2, s16
	buffer_load_dwordx4 v227, s[56:59], s86 offen lds
	s_mov_b32 m0, s20
	s_or_b32 s22, s76, 0xc00
	buffer_load_dwordx4 v227, s[52:55], s2 offen lds
	s_add_i32 s21, s86, s16
	s_mov_b32 m0, s22
	s_add_i32 s23, s76, 0x8c00
	s_add_i32 s2, s2, s16
	buffer_load_dwordx4 v229, s[56:59], s21 offen lds
	s_mov_b32 m0, s23
	v_writelane_b32 v254, s3, 42
	buffer_load_dwordx4 v229, s[52:55], s2 offen lds
	s_add_i32 m0, s76, 0x10000
	s_add_i32 s2, s96, 0x80
	buffer_load_dwordx4 v227, s[56:59], s2 offen lds
	s_add_i32 m0, s76, 0x18000
	s_add_i32 s2, s5, 0x80
	buffer_load_dwordx4 v227, s[52:55], s2 offen lds
	s_add_i32 m0, s76, 0x10400
	s_add_i32 s2, s12, 0x80
	buffer_load_dwordx4 v229, s[56:59], s2 offen lds
	s_add_i32 m0, s76, 0x18400
	s_add_i32 s2, s5, s16
	s_addk_i32 s2, 0x80
	buffer_load_dwordx4 v229, s[52:55], s2 offen lds
	s_add_i32 m0, s76, 0x10800
	s_add_i32 s2, s86, 0x80
	buffer_load_dwordx4 v227, s[56:59], s2 offen lds
	s_add_i32 m0, s76, 0x18800
	s_add_i32 s2, s5, s16
	s_add_i32 s2, s2, s16
	s_addk_i32 s2, 0x80
	buffer_load_dwordx4 v227, s[52:55], s2 offen lds
	s_add_i32 m0, s76, 0x10c00
	s_add_i32 s2, s21, 0x80
	buffer_load_dwordx4 v229, s[56:59], s2 offen lds
	s_add_i32 m0, s76, 0x18c00
	s_add_i32 s2, s5, s16
	s_add_i32 s2, s2, s16
	s_add_i32 s2, s2, s16
	s_addk_i32 s2, 0x80
	buffer_load_dwordx4 v229, s[52:55], s2 offen lds
	s_add_u32 s2, s26, 0x1000000
	s_addc_u32 s3, s27, 0
	v_writelane_b32 v254, s2, 43
	v_or_b32_e32 v2, s0, v2
	v_lshrrev_b32_e32 v4, 1, v0
	v_writelane_b32 v254, s3, 44
	s_add_u32 s2, s26, 0x8880000
	s_addc_u32 s3, s27, 0
	v_writelane_b32 v254, s2, 45
	v_bfe_u32 v0, v0, 1, 3
	v_bitop3_b32 v4, v3, v4, 7 bitop3:0x78
	v_writelane_b32 v254, s3, 46
	s_add_u32 s2, s26, 0xe00000
	s_addc_u32 s3, s27, 0
	v_writelane_b32 v254, s2, 47
	v_bitop3_b32 v0, v3, v0, 4 bitop3:0x36
	v_lshlrev_b32_e32 v2, 7, v2
	v_writelane_b32 v254, s3, 48
	s_add_u32 s2, s26, 0x800000
	s_addc_u32 s3, s27, 0
	v_writelane_b32 v254, s2, 49
	v_lshlrev_b32_e32 v5, 7, v5
	v_lshlrev_b32_e32 v4, 4, v4
	v_writelane_b32 v254, s3, 50
	s_add_u32 s2, s26, 0xd880000
	s_addc_u32 s3, s27, 0
	v_writelane_b32 v254, s2, 51
	v_lshlrev_b32_e32 v0, 4, v0
	v_or_b32_e32 v3, 0x8000, v2
	v_writelane_b32 v254, s3, 52
	s_add_u32 s2, s26, 0x600000
	s_addc_u32 s3, s27, 0
	v_writelane_b32 v254, s2, 53
	s_add_u32 s0, s26, 0x5880000
	v_or_b32_e32 v231, v5, v4
	v_writelane_b32 v254, s3, 54
	v_writelane_b32 v254, s0, 55
	s_addc_u32 s0, s27, 0
	v_writelane_b32 v254, s0, 56
	s_mov_b32 s0, 0x500000
	v_readlane_b32 s6, v254, 19
	v_readlane_b32 s7, v254, 20
	s_and_b64 s[2:3], s[6:7], exec
	s_cselect_b32 s0, s0, 0x400000
	s_add_u32 s2, s26, s0
	s_addc_u32 s3, s27, 0
	v_writelane_b32 v254, s2, 57
	v_or_b32_e32 v233, v5, v0
	v_or_b32_e32 v235, v3, v4
	v_writelane_b32 v254, s3, 58
	s_and_b64 s[2:3], s[6:7], exec
	s_cselect_b32 s0, 10, 8
	s_add_u32 s2, s26, 0x7880000
	v_writelane_b32 v254, s0, 59
	s_addc_u32 s3, s27, 0
	v_writelane_b32 v254, s2, 60
	v_or_b32_e32 v237, v3, v0
	v_or_b32_e32 v239, v2, v4
	v_writelane_b32 v254, s3, 61
	s_add_u32 s2, s26, 0x1b00000
	s_addc_u32 s3, s27, 0
	v_writelane_b32 v254, s2, 62
	s_cmp_eq_u32 s10, 0
	s_cselect_b32 s0, 0, 0xb00
	v_writelane_b32 v254, s3, 63
	s_add_i32 s0, s0, s11
	v_readlane_b32 s2, v254, 22
	v_readlane_b32 s3, v254, 23
	s_mov_b32 s4, s2
	s_mul_i32 s2, s2, 3
	s_ashr_i32 s3, s2, 31
	s_lshl_b64 s[2:3], s[2:3], 20
	s_add_u32 s8, s24, s2
	s_addc_u32 s9, s25, s3
	s_add_u32 s2, s8, 0x200000
	v_writelane_b32 v255, s0, 0
	s_addc_u32 s3, s9, 0
	v_writelane_b32 v255, s2, 1
	v_readlane_b32 s58, v254, 40
	v_or_b32_e32 v241, v2, v0
	v_writelane_b32 v255, s3, 2
	s_add_u32 s2, s26, 0x6880000
	s_addc_u32 s3, s27, 0
	v_writelane_b32 v255, s2, 3
	s_mov_b64 s[90:91], s[54:55]
	s_mov_b64 s[92:93], s[54:55]
	v_writelane_b32 v255, s3, 4
	s_add_u32 s2, s8, 0x100000
	s_addc_u32 s3, s9, 0
	v_writelane_b32 v255, s2, 5
	s_add_u32 s0, s26, 0x5080000
	v_readlane_b32 s59, v254, 41
	v_writelane_b32 v255, s3, 6
	v_writelane_b32 v255, s0, 7
	s_addc_u32 s0, s27, 0
	v_writelane_b32 v255, s0, 8
	s_add_u32 s0, s26, 0x4880000
	v_writelane_b32 v255, s0, 9
	s_addc_u32 s0, s27, 0
	v_writelane_b32 v255, s0, 10
	s_and_b64 s[2:3], s[6:7], exec
	s_mov_b32 s0, 0x200000
	s_cselect_b32 s80, s0, 0x400000
	v_writelane_b32 v255, s80, 11
	s_add_u32 s2, s26, 0xb880000
	s_addc_u32 s3, s27, 0
	v_writelane_b32 v255, s81, 12
	v_writelane_b32 v255, s2, 13
	s_mul_i32 s0, s1, 48
	s_waitcnt vmcnt(0)
	v_writelane_b32 v255, s3, 14
	s_lshl_b32 s2, s4, 5
	s_ashr_i32 s3, s2, 31
	s_add_u32 s6, s8, 0x300000
	v_writelane_b32 v255, s8, 15
	s_addc_u32 s7, s9, 0
	s_lshl_b32 s10, s1, 5
	v_writelane_b32 v255, s9, 16
	v_writelane_b32 v255, s6, 17
	s_add_i32 s9, s76, 0x10000
	s_add_i32 s72, s76, 0x18000
	v_writelane_b32 v255, s7, 18
	v_writelane_b32 v255, s0, 19
	s_lshl_b64 s[0:1], s[2:3], 2
	v_writelane_b32 v255, s0, 20
	s_add_i32 s13, s76, 0x10400
	s_add_i32 s85, s76, 0x18400
	s_add_i32 s11, s76, 0x10800
	s_add_i32 s84, s76, 0x18800
	s_add_i32 s8, s76, 0x10c00
	s_add_i32 s34, s76, 0x18c00
	v_writelane_b32 v255, s1, 21
	v_readlane_b32 s4, v253, 0
	s_barrier
	s_branch .LBB0_206
